# GEMM1 runs on workgroups 0-223 (7 rounds); workgroups 224-255 convert the later-needed weights (items 6912-14847) during that phase instead of in P0
# speedup vs baseline: 1.0119x; 1.0119x over previous
_Z10fwd_kernel4Args:
	s_mov_b32 s94, s2
	s_load_dwordx8 s[76:83], s[0:1], 0x80
	s_load_dword s2, s[0:1], 0xb8
	s_load_dwordx4 s[84:87], s[0:1], 0xa0
	s_load_dwordx2 s[88:89], s[0:1], 0xb0
	s_add_u32 s58, s0, 0xb0
	v_and_b32_e32 v165, 0x3ff, v0
	s_addc_u32 s59, s1, 0
	v_cmp_gt_u32_e32 vcc, 2, v165
	s_waitcnt lgkmcnt(0)
	v_writelane_b32 v228, s2, 0
	s_mov_b32 s101, 0
	s_mov_b32 s100, 0
	s_movk_i32 s99, 0x44ff
	s_cmp_lg_u32 s88, 0x100
	s_cbranch_scc1 .Lp0_full
	s_movk_i32 s99, 0x1aff

.LBB0_154:
	s_cmp_eq_u32 s101, 3
	s_cbranch_scc1 .Lp1_conv_ret
	s_cmp_lg_u32 s101, 0
	s_cbranch_scc1 .Ltramp_back
	s_mov_b32 s24, s98
	s_cmpk_gt_i32 s24, 0x23ff
	s_cbranch_scc0 .LBB0_156
	s_branch .LBB0_162
.LBB0_155:
	v_readlane_b32 s88, v228, 6
	v_readlane_b32 s58, v228, 12
	v_readlane_b32 s94, v228, 16
	v_readlane_b32 s89, v228, 7
	v_readlane_b32 s59, v228, 13
	v_readlane_b32 s95, v228, 17
	s_cmp_eq_u32 s101, 3
	s_cbranch_scc1 .Lp1_conv_ret
	s_cmp_lg_u32 s101, 0
	s_cbranch_scc1 .Ltramp_back
	s_mov_b32 s24, s98
	s_lshl_b32 s44, s88, 3
	s_cmpk_gt_i32 s24, 0x23ff
	s_cbranch_scc1 .LBB0_162

.LBB0_248:
.LBB0_249:
	s_cmp_lt_i32 s86, 2
	s_cselect_b64 s[2:3], -1, 0
	s_add_u32 s62, s84, 0xb000000
	s_addc_u32 s63, s85, 0
	s_add_u32 s64, s84, 0xf800000
	s_addc_u32 s65, s85, 0
	s_add_u32 s70, s84, 0x13800000
	s_addc_u32 s71, s85, 0
	s_add_u32 s4, s84, 0x17800000
	s_addc_u32 s5, s85, 0
	s_and_b64 s[0:1], s[2:3], s[0:1]
	v_writelane_b32 v228, s4, 14
	s_andn2_b64 vcc, exec, s[0:1]
	s_nop 0
	v_writelane_b32 v228, s5, 15
	s_cbranch_vccnz .LBB0_392
	s_cmp_lg_u32 s88, 0x100
	s_cbranch_scc1 .Lp1_all
	s_cmp_lt_u32 s94, 0xe0
	s_cbranch_scc1 .Lp1_gemm
	v_readlane_b32 s0, v228, 12
	v_readlane_b32 s1, v228, 13
	s_sub_u32 s0, s0, 0xb0
	s_subb_u32 s1, s1, 0
	s_load_dwordx16 s[60:75], s[0:1], 0x0
	s_load_dwordx4 s[76:79], s[0:1], 0x80
	s_add_i32 s94, s94, 0xa0
	s_mov_b32 s101, 3
	s_movk_i32 s99, 0x39ff
	s_movk_i32 s100, 0x1b00
	s_waitcnt lgkmcnt(0)
	s_branch .Lp0_entry
.Lp1_conv_ret:
	s_sub_i32 s94, s94, 0xa0
	s_mov_b32 s101, 0
	s_add_u32 s62, s84, 0xb000000
	s_addc_u32 s63, s85, 0
	s_add_u32 s64, s84, 0xf800000
	s_addc_u32 s65, s85, 0
	s_add_u32 s70, s84, 0x13800000
	s_addc_u32 s71, s85, 0
	s_add_u32 s4, s84, 0x17800000
	s_addc_u32 s5, s85, 0
	s_nop 0
	v_writelane_b32 v228, s94, 16
	v_writelane_b32 v228, s4, 14
	v_writelane_b32 v228, s5, 15
	s_waitcnt vmcnt(0) lgkmcnt(0)
	s_barrier
	s_mov_b64 s[0:1], -1
	s_branch .LBB0_392
.Lp1_gemm:
	s_movk_i32 s88, 0xe0
.Lp1_all:
	s_add_u32 s3, s84, 0x200000
	s_addc_u32 s34, s85, 0
	s_abs_i32 s2, s88
	v_cvt_f32_u32_e32 v1, s2
	s_sub_i32 s5, 0, s2
	s_ashr_i32 s4, s88, 31
	v_readfirstlane_b32 s10, v165
	v_rcp_iflag_f32_e32 v1, v1
	s_nop 0
	v_mul_f32_e32 v1, 0x4f7ffffe, v1
	v_cvt_u32_f32_e32 v1, v1
	s_nop 0
	v_readfirstlane_b32 s6, v1
	s_mul_i32 s5, s5, s6
	s_mul_hi_u32 s5, s6, s5
	s_add_i32 s6, s6, s5
	s_mul_hi_u32 s5, s6, 0x600
	s_mul_i32 s6, s5, s2
	s_sub_i32 s6, 0x600, s6
	s_add_i32 s7, s5, 1
	s_sub_i32 s8, s6, s2
	s_cmp_ge_u32 s6, s2
	s_cselect_b32 s5, s7, s5
	s_cselect_b32 s6, s8, s6
	s_add_i32 s7, s5, 1
	s_cmp_ge_u32 s6, s2
	s_cselect_b32 s2, s7, s5
	s_xor_b32 s2, s2, s4
	s_sub_i32 s35, s2, s4
	s_mul_i32 s2, s35, s88
	s_sub_i32 s12, 0x600, s2
	s_cmp_lt_i32 s94, s12
	s_cselect_b64 s[4:5], -1, 0
	s_cmp_gt_i32 s35, 0
	s_mov_b64 s[6:7], -1
	s_mov_b32 s8, s94
	s_cbranch_scc1 .LBB0_253
	s_cmp_eq_u32 s35, 0
	s_cselect_b64 s[6:7], -1, 0
	s_and_b64 s[6:7], s[6:7], s[4:5]
	s_and_b64 vcc, exec, s[6:7]
	s_cbranch_vccz .LBB0_256
	s_abs_i32 s6, s12
	v_cvt_f32_u32_e32 v1, s6
	s_sub_i32 s9, 0, s6
	s_abs_i32 s8, s94
	s_ashr_i32 s7, s94, 31
	v_rcp_iflag_f32_e32 v1, v1
	s_nop 0
	v_mul_f32_e32 v1, 0x4f7ffffe, v1
	v_cvt_u32_f32_e32 v1, v1
	s_nop 0
	v_readfirstlane_b32 s11, v1
	s_mul_i32 s9, s9, s11
	s_mul_hi_u32 s9, s11, s9
	s_add_i32 s11, s11, s9
	s_mul_hi_u32 s9, s8, s11
	s_mul_i32 s9, s9, s6
	s_sub_i32 s8, s8, s9
	s_sub_i32 s9, s8, s6
	s_cmp_ge_u32 s8, s6
	s_cselect_b32 s8, s9, s8
	s_sub_i32 s9, s8, s6
	s_cmp_ge_u32 s8, s6
	s_cselect_b32 s6, s9, s8
	s_xor_b32 s6, s6, s7
	s_sub_i32 s8, s6, s7
	s_mov_b64 s[6:7], -1

.LBB0_392:
	v_readlane_b32 s88, v228, 6
	s_cmp_gt_i32 s87, 2
	s_cselect_b64 s[4:5], -1, 0
	s_and_b64 s[0:1], s[0:1], s[4:5]
	s_andn2_b64 vcc, exec, s[0:1]
	s_cbranch_vccnz .LBB0_460
	s_cmp_gt_i32 s86, -1
	s_mov_b64 s[0:1], -1
	s_cbranch_scc0 .LBB0_447
	s_waitcnt vmcnt(0)
	s_waitcnt vmcnt(0)
	s_barrier
	s_mov_b64 s[0:1], exec
	v_readlane_b32 s2, v228, 4
	v_readlane_b32 s3, v228, 5
	s_and_b64 s[2:3], s[0:1], s[2:3]
	s_mov_b64 exec, s[2:3]
	s_cbranch_execz .LBB0_446
	s_add_i32 s2, 0, 0x23fc0
	v_mov_b32_e32 v1, s2
	s_waitcnt vmcnt(0) expcnt(0) lgkmcnt(0)
	ds_read_b32 v3, v1
	s_add_i32 s2, 0, 0x23fc4
	v_mov_b32_e32 v1, s2
	ds_read_b32 v1, v1
	s_waitcnt lgkmcnt(1)
	v_cmp_ne_u32_e32 vcc, 0, v3
	s_cbranch_vccnz .LBB0_410
	s_add_u32 s6, s84, 0x30200
	s_addc_u32 s7, s85, 0
	s_add_u32 s8, s84, 0x30400
	s_addc_u32 s9, s85, 0
	s_add_u32 s10, s84, 0x30500
	s_addc_u32 s11, s85, 0
	s_add_u32 s12, s84, 0x30600
	s_addc_u32 s13, s85, 0
	s_add_u32 s14, s84, 0x30700
	s_addc_u32 s15, s85, 0
	s_add_u32 s16, s84, 0x30800
	s_addc_u32 s17, s85, 0
	s_add_u32 s18, s84, 0x30900
	s_addc_u32 s19, s85, 0
	s_add_u32 s20, s84, 0x30a00
	s_addc_u32 s21, s85, 0
	s_add_u32 s22, s84, 0x30b00
	s_addc_u32 s23, s85, 0
	s_add_u32 s24, s84, 0x30c00
	s_addc_u32 s25, s85, 0
	s_add_u32 s26, s84, 0x30d00
	s_addc_u32 s27, s85, 0
	s_add_u32 s28, s84, 0x30e00
	s_addc_u32 s29, s85, 0
	s_add_u32 s30, s84, 0x30f00
	s_addc_u32 s31, s85, 0
	s_add_u32 s34, s84, 0x31000
	s_addc_u32 s35, s85, 0
	s_add_u32 s36, s84, 0x31100
	s_addc_u32 s37, s85, 0
	s_add_u32 s38, s84, 0x31200
	v_readlane_b32 s2, v228, 0
	s_addc_u32 s39, s85, 0
	s_mul_i32 s2, s89, s2
	s_add_u32 s40, s84, 0x31300
	s_mul_i32 s2, s2, s88
	s_addc_u32 s41, s85, 0
	s_mov_b32 s3, 1
	v_mov_b32_e32 v17, 0
	s_branch .LBB0_398
